# grid barrier: non-leader workgroups poll their XCD generation word with two loads in flight (shorter detection delay) instead of one load per sleep-spin
# baseline (speedup 1.0000x reference)
; __device__ __forceinline__ unsigned xb_ld(unsigned* p)              { return __hip_atomic_load(p, __ATOMIC_RELAXED, __HIP_MEMORY_SCOPE_AGENT); }
; #define XB_SPIN(cond, bar) do { unsigned _sp = 0; while (cond) { __builtin_amdgcn_s_sleep(1); \
;     if ((++_sp & 255u) == 0u) { if (xb_ld(&(bar)[XB_TMO])) break; if (_sp > XB_SPIN_CAP) { atomicAdd(&(bar)[XB_TMO], 1u); break; } } } } while (0)
; __device__ __forceinline__ void xcd_barrier(unsigned* bar, unsigned x, volatile LAS unsigned* st) {
;     ...
;         } else {
;             XB_SPIN(xb_ld(&bar[XB_XGEN(x)]) == gen, bar);
;             __builtin_amdgcn_fence(__ATOMIC_ACQUIRE, "agent");
;             asm volatile("s_waitcnt vmcnt(0)" ::: "memory");
.LBB0_864:
	s_or_b64 exec, exec, s[8:9]
	v_cvt_f32_u32_e32 v4, v2
	s_waitcnt vmcnt(0)
	v_readfirstlane_b32 s2, v3
	v_sub_u32_e32 v3, 0, v2
	v_rcp_iflag_f32_e32 v4, v4
	v_add_u32_e32 v5, s2, v1
	v_mul_f32_e32 v4, 0x4f7ffffe, v4
	v_cvt_u32_f32_e32 v4, v4
	v_mul_lo_u32 v1, v3, v4
	v_mul_hi_u32 v1, v4, v1
	v_add_u32_e32 v1, v4, v1
	v_mul_hi_u32 v1, v5, v1
	v_mul_lo_u32 v3, v1, v2
	v_sub_u32_e32 v3, v5, v3
	v_add_u32_e32 v4, 1, v1
	v_cmp_ge_u32_e32 vcc, v3, v2
	s_nop 1
	v_cndmask_b32_e32 v1, v1, v4, vcc
	v_sub_u32_e32 v4, v3, v2
	v_cndmask_b32_e32 v3, v3, v4, vcc
	v_add_u32_e32 v4, 1, v1
	v_cmp_ge_u32_e32 vcc, v3, v2
	v_add_u32_e32 v3, 1, v5
	s_nop 0
	v_cndmask_b32_e32 v1, v1, v4, vcc
	v_mul_lo_u32 v4, v2, v1
	v_add_u32_e32 v2, v4, v2
	v_cmp_ne_u32_e32 vcc, v3, v2
	s_and_saveexec_b64 s[2:3], vcc
	s_xor_b64 s[6:7], exec, s[2:3]
	s_cbranch_execz .LBB0_878
	s_waitcnt lgkmcnt(0)
	global_load_dword v0, v194, s[4:5] offset:1024 sc1
	s_add_u32 s10, s4, 0x2400
	s_addc_u32 s11, s5, 0
	s_waitcnt vmcnt(0)
	v_cmp_eq_u32_e32 vcc, v0, v1
	s_and_saveexec_b64 s[8:9], vcc
	s_cbranch_execz .LBB0_877
	s_mov_b32 s2, 0x40000
	global_load_dword v0, v33, s[10:11] sc1
.Lnl_loop:
	s_sleep 4
	global_load_dword v2, v33, s[10:11] sc1
	s_waitcnt vmcnt(1)
	v_cmp_ne_u32_e32 vcc, v0, v1
	s_cbranch_vccnz .LBB0_877
	s_sleep 4
	global_load_dword v0, v33, s[10:11] sc1
	s_waitcnt vmcnt(1)
	v_cmp_ne_u32_e32 vcc, v2, v1
	s_cbranch_vccnz .LBB0_877
	s_sub_i32 s2, s2, 1
	s_cmp_lg_u32 s2, 0
	s_cbranch_scc1 .Lnl_loop
